# v034 + HGRN: token-row addresses for tokens 1-7 derived by a 64-bit +/-1024 add from token 0 instead of nine scalar ops each
# speedup vs baseline: 1.0043x; 1.0043x over previous
; #define LAS __attribute__((address_space(3)))
; __device__ __forceinline__ float bflo(unsigned u) { return __uint_as_float(u << 16); }
; __device__ __forceinline__ float bfhi(unsigned u) { return __uint_as_float(u & 0xffff0000u); }
; #define HG_LOAD(c_, q_, k_, v_) do { _Pragma("unroll") for (int j = 0; j < 8; ++j) { const size_t off = (tok0 + HG_TOK(c_, 8 * wid + j)) * 512 + hh * 128 + 2 * lane; \
;         q_[j] = *(const unsigned*)(QR + off); k_[j] = *(const unsigned*)(KK + off); } \
;         v_ = *(const u32x4*)(IR + (tok0 + HG_TOK(c_, tv)) * 512 + hh * 128 + dvh * 64 + cv * 8); } while (0)
; __device__ __forceinline__ void hgrn_phase(LAS unsigned char* lds, const bf16_t* mix, bf16_t* OFB, int item) {
;     ...
;     HG_LOAD(0, cq, ck, cvv);
;     __syncthreads();
;     for (int c = 0; c < 64; ++c) {
;         float c0[8], c1[8];
;         { float a0 = 1.f, a1 = 1.f;
; #pragma unroll
;           for (int j = 0; j < 8; ++j) { a0 *= 1.0f - bflo(ck[j]); a1 *= 1.0f - bfhi(ck[j]); c0[j] = a0; c1[j] = a1; } }
;         *(LAS f32x2*)(lds + HG_SEG + (wid * 128 + 2 * lane) * 4) = (f32x2){c0[7], c1[7]};
;         unsigned nq[8], nk[8]; u32x4 nv;
;         { const int cn = (c + 1 < 64) ? c + 1 : 63; HG_LOAD(cn, nq, nk, nv); }
.LBB0_507:
	s_and_b64 s[100:101], s[4:5], exec
	s_movk_i32 s100, 0x400
	s_cselect_b32 s98, s100, 0xfffffc00
	s_cselect_b32 s99, 0, -1
	s_add_i32 s74, s78, 1
	s_cmp_lg_u32 s78, 63
	s_cselect_b32 s92, s74, 63
	s_lshl_b32 s75, s92, 6
	s_add_i32 s93, s75, s33
	s_sub_i32 vcc_lo, 0xfff, s93
	s_and_b64 s[56:57], s[4:5], exec
	s_cselect_b32 s56, s93, vcc_lo
	s_ashr_i32 s57, s56, 31
	s_add_u32 s56, s90, s56
	s_addc_u32 s57, s91, s57
	s_lshl_b64 s[56:57], s[56:57], 10
	v_or_b32_e32 v38, s56, v80
	v_mov_b32_e32 v39, s57
	s_add_u32 s56, s56, s98
	s_addc_u32 s57, s57, s99
	v_or_b32_e32 v42, s56, v80
	v_mov_b32_e32 v43, s57
	s_add_u32 s56, s56, s98
	s_addc_u32 s57, s57, s99
	v_or_b32_e32 v46, s56, v80
	v_mov_b32_e32 v47, s57
	s_add_u32 s56, s56, s98
	s_addc_u32 s57, s57, s99
	v_or_b32_e32 v50, s56, v80
	v_mov_b32_e32 v51, s57
	s_add_u32 s56, s56, s98
	s_addc_u32 s57, s57, s99
	v_lshl_add_u64 v[40:41], s[82:83], 0, v[38:39]
	v_lshl_add_u64 v[38:39], s[88:89], 0, v[38:39]
	s_waitcnt vmcnt(15)
	v_lshlrev_b32_e32 v36, 16, v75
	v_and_b32_e32 v37, 0xffff0000, v75
	s_waitcnt vmcnt(13)
	v_lshlrev_b32_e32 v34, 16, v76
	v_and_b32_e32 v35, 0xffff0000, v76
	s_waitcnt vmcnt(11)
	v_lshlrev_b32_e32 v32, 16, v77
	v_and_b32_e32 v33, 0xffff0000, v77
	s_waitcnt vmcnt(9)
	v_lshlrev_b32_e32 v14, 16, v78
	v_and_b32_e32 v15, 0xffff0000, v78
	v_lshl_add_u64 v[44:45], s[82:83], 0, v[42:43]
	v_lshl_add_u64 v[42:43], s[88:89], 0, v[42:43]
	v_lshl_add_u64 v[48:49], s[82:83], 0, v[46:47]
	v_lshl_add_u64 v[46:47], s[88:89], 0, v[46:47]
	v_lshl_add_u64 v[58:59], s[82:83], 0, v[50:51]
	v_lshl_add_u64 v[50:51], s[88:89], 0, v[50:51]
	global_load_dword v92, v[40:41], off
	global_load_dword v75, v[38:39], off
	global_load_dword v93, v[44:45], off
	global_load_dword v76, v[42:43], off
	global_load_dword v94, v[48:49], off
	global_load_dword v77, v[46:47], off
	global_load_dword v95, v[58:59], off
	global_load_dword v78, v[50:51], off
	v_or_b32_e32 v38, s56, v80
	v_mov_b32_e32 v39, s57
	s_add_u32 s56, s56, s98
	s_addc_u32 s57, s57, s99
	v_or_b32_e32 v42, s56, v80
	v_mov_b32_e32 v43, s57
	s_add_u32 s56, s56, s98
	s_addc_u32 s57, s57, s99
	v_or_b32_e32 v46, s56, v80
	v_mov_b32_e32 v47, s57
	s_add_u32 s56, s56, s98
	s_addc_u32 s57, s57, s99
	v_lshl_add_u64 v[40:41], s[82:83], 0, v[38:39]
	v_or_b32_e32 v50, s56, v80
	v_mov_b32_e32 v51, s57
	s_waitcnt vmcnt(15)
	v_lshlrev_b32_e32 v12, 16, v89
	v_and_b32_e32 v13, 0xffff0000, v89
	s_waitcnt vmcnt(13)
	v_lshlrev_b32_e32 v10, 16, v90
	v_and_b32_e32 v11, 0xffff0000, v90
	s_waitcnt vmcnt(11)
	v_lshlrev_b32_e32 v8, 16, v91
	v_and_b32_e32 v9, 0xffff0000, v91
	s_waitcnt vmcnt(9)
	v_lshlrev_b32_e32 v6, 16, v88
	v_and_b32_e32 v7, 0xffff0000, v88
	v_lshl_add_u64 v[38:39], s[88:89], 0, v[38:39]
	v_lshl_add_u64 v[44:45], s[82:83], 0, v[42:43]
	v_lshl_add_u64 v[42:43], s[88:89], 0, v[42:43]
	v_lshl_add_u64 v[48:49], s[82:83], 0, v[46:47]
	v_lshl_add_u64 v[46:47], s[88:89], 0, v[46:47]
	v_lshl_add_u64 v[58:59], s[82:83], 0, v[50:51]
	v_lshl_add_u64 v[50:51], s[88:89], 0, v[50:51]
	global_load_dword v96, v[40:41], off
	global_load_dword v89, v[38:39], off
	global_load_dword v97, v[44:45], off
	global_load_dword v90, v[42:43], off
	global_load_dword v98, v[48:49], off
	global_load_dword v91, v[46:47], off
	global_load_dword v99, v[58:59], off
	global_load_dword v88, v[50:51], off
	v_pk_add_f32 v[64:65], v[36:37], 1.0 op_sel_hi:[1,0] neg_lo:[1,0] neg_hi:[1,0]
	v_pk_add_f32 v[38:39], v[34:35], 1.0 op_sel_hi:[1,0] neg_lo:[1,0] neg_hi:[1,0]
	v_add_u32_e32 v44, s79, v69
	v_pk_mul_f32 v[62:63], v[64:65], v[38:39]
	v_pk_add_f32 v[38:39], v[32:33], 1.0 op_sel_hi:[1,0] neg_lo:[1,0] neg_hi:[1,0]
	s_andn2_b64 vcc, exec, s[64:65]
	v_pk_mul_f32 v[60:61], v[62:63], v[38:39]
	v_pk_add_f32 v[38:39], v[14:15], 1.0 op_sel_hi:[1,0] neg_lo:[1,0] neg_hi:[1,0]
	s_mov_b64 s[56:57], -1
	v_pk_mul_f32 v[58:59], v[60:61], v[38:39]
	v_pk_add_f32 v[38:39], v[12:13], 1.0 op_sel_hi:[1,0] neg_lo:[1,0] neg_hi:[1,0]
	s_nop 0
	v_pk_mul_f32 v[46:47], v[58:59], v[38:39]
	v_pk_add_f32 v[38:39], v[10:11], 1.0 op_sel_hi:[1,0] neg_lo:[1,0] neg_hi:[1,0]
	s_nop 0
	v_pk_mul_f32 v[42:43], v[46:47], v[38:39]
	v_pk_add_f32 v[38:39], v[8:9], 1.0 op_sel_hi:[1,0] neg_lo:[1,0] neg_hi:[1,0]
	s_nop 0
	v_pk_mul_f32 v[40:41], v[42:43], v[38:39]
	v_pk_add_f32 v[38:39], v[6:7], 1.0 op_sel_hi:[1,0] neg_lo:[1,0] neg_hi:[1,0]
	s_nop 0
	v_pk_mul_f32 v[38:39], v[40:41], v[38:39]
	ds_write_b64 v44, v[38:39]
	s_cbranch_vccnz .LBB0_509
	v_lshl_add_u32 v44, s92, 6, v68
	v_sub_u32_e32 v44, 0xfff, v44
	s_mov_b64 s[56:57], 0
